# early L2 write-back by arriver 26 (instead of 20) + TOP poll
# baseline (speedup 1.0000x reference)
.LBB0_140:
	s_or_b64 exec, exec, s[8:9]
	v_cvt_f32_u32_e32 v4, v2
	s_waitcnt vmcnt(0)
	v_readfirstlane_b32 s3, v3
	v_sub_u32_e32 v3, 0, v2
	v_rcp_iflag_f32_e32 v4, v4
	v_add_u32_e32 v5, s3, v1
	v_mul_f32_e32 v4, 0x4f7ffffe, v4
	v_cvt_u32_f32_e32 v4, v4
	v_mul_lo_u32 v1, v3, v4
	v_mul_hi_u32 v1, v4, v1
	v_add_u32_e32 v1, v4, v1
	v_mul_hi_u32 v1, v5, v1
	v_mul_lo_u32 v3, v1, v2
	v_sub_u32_e32 v3, v5, v3
	v_add_u32_e32 v4, 1, v1
	v_cmp_ge_u32_e32 vcc, v3, v2
	s_nop 1
	v_cndmask_b32_e32 v1, v1, v4, vcc
	v_sub_u32_e32 v4, v3, v2
	v_cndmask_b32_e32 v3, v3, v4, vcc
	v_add_u32_e32 v4, 1, v1
	v_cmp_ge_u32_e32 vcc, v3, v2
	v_add_u32_e32 v3, 1, v5
	s_nop 0
	v_cndmask_b32_e32 v1, v1, v4, vcc
	v_mul_lo_u32 v4, v2, v1
	v_add_u32_e32 v2, v4, v2
	v_cmp_ne_u32_e32 vcc, v3, v2
	s_and_saveexec_b64 s[6:7], vcc
	s_xor_b64 s[6:7], exec, s[6:7]
	s_cbranch_execz .LBB0_154
	s_waitcnt lgkmcnt(0)
	v_mov_b32_e32 v0, 0x2000
	buffer_inv sc1
	v_readfirstlane_b32 s12, v5
	s_and_b32 s12, s12, 31
	s_cmp_eq_u32 s12, 26
	s_cbranch_scc0 .Lewb_skip1

.LBB0_939:
	s_or_b64 exec, exec, s[16:17]
	v_cvt_f32_u32_e32 v4, v2
	s_waitcnt vmcnt(0)
	v_readfirstlane_b32 s2, v3
	v_sub_u32_e32 v3, 0, v2
	v_rcp_iflag_f32_e32 v4, v4
	v_add_u32_e32 v5, s2, v1
	v_mul_f32_e32 v4, 0x4f7ffffe, v4
	v_cvt_u32_f32_e32 v4, v4
	v_mul_lo_u32 v1, v3, v4
	v_mul_hi_u32 v1, v4, v1
	v_add_u32_e32 v1, v4, v1
	v_mul_hi_u32 v1, v5, v1
	v_mul_lo_u32 v3, v1, v2
	v_sub_u32_e32 v3, v5, v3
	v_add_u32_e32 v4, 1, v1
	v_cmp_ge_u32_e32 vcc, v3, v2
	s_nop 1
	v_cndmask_b32_e32 v1, v1, v4, vcc
	v_sub_u32_e32 v4, v3, v2
	v_cndmask_b32_e32 v3, v3, v4, vcc
	v_add_u32_e32 v4, 1, v1
	v_cmp_ge_u32_e32 vcc, v3, v2
	v_add_u32_e32 v3, 1, v5
	s_nop 0
	v_cndmask_b32_e32 v1, v1, v4, vcc
	v_mul_lo_u32 v4, v2, v1
	v_add_u32_e32 v2, v4, v2
	v_cmp_ne_u32_e32 vcc, v3, v2
	s_and_saveexec_b64 s[8:9], vcc
	s_xor_b64 s[14:15], exec, s[8:9]
	s_cbranch_execz .LBB0_953
	s_waitcnt lgkmcnt(0)
	buffer_inv sc1
	v_readfirstlane_b32 s18, v5
	s_and_b32 s18, s18, 31
	s_cmp_eq_u32 s18, 26
	s_cbranch_scc0 .Lewb_skip2

.LBB0_1593:
	s_or_b64 exec, exec, s[18:19]
	v_cvt_f32_u32_e32 v4, v2
	s_waitcnt vmcnt(0)
	v_readfirstlane_b32 s2, v3
	v_sub_u32_e32 v3, 0, v2
	v_rcp_iflag_f32_e32 v4, v4
	v_add_u32_e32 v5, s2, v1
	v_mul_f32_e32 v4, 0x4f7ffffe, v4
	v_cvt_u32_f32_e32 v4, v4
	v_mul_lo_u32 v1, v3, v4
	v_mul_hi_u32 v1, v4, v1
	v_add_u32_e32 v1, v4, v1
	v_mul_hi_u32 v1, v5, v1
	v_mul_lo_u32 v3, v1, v2
	v_sub_u32_e32 v3, v5, v3
	v_add_u32_e32 v4, 1, v1
	v_cmp_ge_u32_e32 vcc, v3, v2
	s_nop 1
	v_cndmask_b32_e32 v1, v1, v4, vcc
	v_sub_u32_e32 v4, v3, v2
	v_cndmask_b32_e32 v3, v3, v4, vcc
	v_add_u32_e32 v4, 1, v1
	v_cmp_ge_u32_e32 vcc, v3, v2
	v_add_u32_e32 v3, 1, v5
	s_nop 0
	v_cndmask_b32_e32 v1, v1, v4, vcc
	v_mul_lo_u32 v4, v2, v1
	v_add_u32_e32 v2, v4, v2
	v_cmp_ne_u32_e32 vcc, v3, v2
	s_and_saveexec_b64 s[8:9], vcc
	s_xor_b64 s[16:17], exec, s[8:9]
	s_cbranch_execz .LBB0_1607
	s_waitcnt lgkmcnt(0)
	buffer_inv sc1
	v_readfirstlane_b32 s20, v5
	s_and_b32 s20, s20, 31
	s_cmp_eq_u32 s20, 26
	s_cbranch_scc0 .Lewb_skip5

.LBB0_1713:
	s_or_b64 exec, exec, s[16:17]
	v_cvt_f32_u32_e32 v4, v2
	s_waitcnt vmcnt(0)
	v_readfirstlane_b32 s8, v3
	v_sub_u32_e32 v3, 0, v2
	v_rcp_iflag_f32_e32 v4, v4
	v_add_u32_e32 v5, s8, v1
	v_mul_f32_e32 v4, 0x4f7ffffe, v4
	v_cvt_u32_f32_e32 v4, v4
	v_mul_lo_u32 v1, v3, v4
	v_mul_hi_u32 v1, v4, v1
	v_add_u32_e32 v1, v4, v1
	v_mul_hi_u32 v1, v5, v1
	v_mul_lo_u32 v3, v1, v2
	v_sub_u32_e32 v3, v5, v3
	v_add_u32_e32 v4, 1, v1
	v_cmp_ge_u32_e32 vcc, v3, v2
	s_nop 1
	v_cndmask_b32_e32 v1, v1, v4, vcc
	v_sub_u32_e32 v4, v3, v2
	v_cndmask_b32_e32 v3, v3, v4, vcc
	v_add_u32_e32 v4, 1, v1
	v_cmp_ge_u32_e32 vcc, v3, v2
	v_add_u32_e32 v3, 1, v5
	s_nop 0
	v_cndmask_b32_e32 v1, v1, v4, vcc
	v_mul_lo_u32 v4, v2, v1
	v_add_u32_e32 v2, v4, v2
	v_cmp_ne_u32_e32 vcc, v3, v2
	s_and_saveexec_b64 s[8:9], vcc
	s_xor_b64 s[14:15], exec, s[8:9]
	s_cbranch_execz .LBB0_1727
	s_waitcnt lgkmcnt(0)
	buffer_inv sc1
	v_readfirstlane_b32 s18, v5
	s_and_b32 s18, s18, 31
	s_cmp_eq_u32 s18, 26
	s_cbranch_scc0 .Lewb_skip6
